# prep weight transposes: w_in / w_out / wq tile load loops made straight-line with all 16 loads of a tile in flight
# speedup vs baseline: 1.1695x; 1.0148x over previous
.LBB0_23:
	s_cmpk_gt_u32 s37, 0x38f
	s_cbranch_scc0 .LBB0_64
	s_ashr_i32 s11, s10, 31
	s_lshl_b64 s[6:7], s[10:11], 20
	s_and_b32 s11, s37, 15
	s_cmpk_gt_u32 s37, 0x48f
	s_cbranch_scc0 .LBB0_44
	s_add_i32 s4, s37, 0xfffffb70
	v_mov_b32_e32 v2, v172
	s_lshr_b32 s38, s4, 4
	s_nop 0
	v_cmp_gt_i32_e32 vcc, s26, v2
	s_and_saveexec_b64 s[18:19], vcc
	s_cbranch_execz .LBB0_38
	s_load_dwordx16 s[56:71], s[0:1], 0x140
	s_lshl_b64 s[4:5], s[6:7], 2
	v_lshlrev_b32_e32 v0, 2, v2
	v_and_b32_e32 v4, 0xfc, v0
	v_lshl_or_b32 v0, s11, 8, v4
	s_waitcnt lgkmcnt(0)
	s_add_u32 s4, s60, s4
	s_addc_u32 s5, s61, s5
	v_lshl_add_u64 v[6:7], s[4:5], 0, v[0:1]
	s_lshl_b32 s39, s38, 6
	v_ashrrev_i32_e32 v58, 6, v2
	v_add_u32_e32 v59, s39, v58
	v_mov_b32_e32 v78, v59
	v_mov_b32_e32 v79, 0
	v_lshlrev_b64 v[78:79], 12, v[78:79]
	v_lshl_add_u64 v[78:79], v[6:7], 0, v[78:79]
	global_load_dword v60, v[78:79], off
	v_add_u32_e32 v76, 4, v59
	v_mov_b32_e32 v80, v76
	v_mov_b32_e32 v81, 0
	v_lshlrev_b64 v[80:81], 12, v[80:81]
	v_lshl_add_u64 v[80:81], v[6:7], 0, v[80:81]
	global_load_dword v61, v[80:81], off
	v_add_u32_e32 v76, 8, v59
	v_mov_b32_e32 v82, v76
	v_mov_b32_e32 v83, 0
	v_lshlrev_b64 v[82:83], 12, v[82:83]
	v_lshl_add_u64 v[82:83], v[6:7], 0, v[82:83]
	global_load_dword v62, v[82:83], off
	v_add_u32_e32 v76, 12, v59
	v_mov_b32_e32 v84, v76
	v_mov_b32_e32 v85, 0
	v_lshlrev_b64 v[84:85], 12, v[84:85]
	v_lshl_add_u64 v[84:85], v[6:7], 0, v[84:85]
	global_load_dword v63, v[84:85], off
	v_add_u32_e32 v76, 16, v59
	v_mov_b32_e32 v78, v76
	v_mov_b32_e32 v79, 0
	v_lshlrev_b64 v[78:79], 12, v[78:79]
	v_lshl_add_u64 v[78:79], v[6:7], 0, v[78:79]
	global_load_dword v64, v[78:79], off
	v_add_u32_e32 v76, 20, v59
	v_mov_b32_e32 v80, v76
	v_mov_b32_e32 v81, 0
	v_lshlrev_b64 v[80:81], 12, v[80:81]
	v_lshl_add_u64 v[80:81], v[6:7], 0, v[80:81]
	global_load_dword v65, v[80:81], off
	v_add_u32_e32 v76, 24, v59
	v_mov_b32_e32 v82, v76
	v_mov_b32_e32 v83, 0
	v_lshlrev_b64 v[82:83], 12, v[82:83]
	v_lshl_add_u64 v[82:83], v[6:7], 0, v[82:83]
	global_load_dword v66, v[82:83], off
	v_add_u32_e32 v76, 28, v59
	v_mov_b32_e32 v84, v76
	v_mov_b32_e32 v85, 0
	v_lshlrev_b64 v[84:85], 12, v[84:85]
	v_lshl_add_u64 v[84:85], v[6:7], 0, v[84:85]
	global_load_dword v67, v[84:85], off
	v_add_u32_e32 v76, 32, v59
	v_mov_b32_e32 v78, v76
	v_mov_b32_e32 v79, 0
	v_lshlrev_b64 v[78:79], 12, v[78:79]
	v_lshl_add_u64 v[78:79], v[6:7], 0, v[78:79]
	global_load_dword v68, v[78:79], off
	v_add_u32_e32 v76, 36, v59
	v_mov_b32_e32 v80, v76
	v_mov_b32_e32 v81, 0
	v_lshlrev_b64 v[80:81], 12, v[80:81]
	v_lshl_add_u64 v[80:81], v[6:7], 0, v[80:81]
	global_load_dword v69, v[80:81], off
	v_add_u32_e32 v76, 40, v59
	v_mov_b32_e32 v82, v76
	v_mov_b32_e32 v83, 0
	v_lshlrev_b64 v[82:83], 12, v[82:83]
	v_lshl_add_u64 v[82:83], v[6:7], 0, v[82:83]
	global_load_dword v70, v[82:83], off
	v_add_u32_e32 v76, 44, v59
	v_mov_b32_e32 v84, v76
	v_mov_b32_e32 v85, 0
	v_lshlrev_b64 v[84:85], 12, v[84:85]
	v_lshl_add_u64 v[84:85], v[6:7], 0, v[84:85]
	global_load_dword v71, v[84:85], off
	v_add_u32_e32 v76, 48, v59
	v_mov_b32_e32 v78, v76
	v_mov_b32_e32 v79, 0
	v_lshlrev_b64 v[78:79], 12, v[78:79]
	v_lshl_add_u64 v[78:79], v[6:7], 0, v[78:79]
	global_load_dword v72, v[78:79], off
	v_add_u32_e32 v76, 52, v59
	v_mov_b32_e32 v80, v76
	v_mov_b32_e32 v81, 0
	v_lshlrev_b64 v[80:81], 12, v[80:81]
	v_lshl_add_u64 v[80:81], v[6:7], 0, v[80:81]
	global_load_dword v73, v[80:81], off
	v_add_u32_e32 v76, 56, v59
	v_mov_b32_e32 v82, v76
	v_mov_b32_e32 v83, 0
	v_lshlrev_b64 v[82:83], 12, v[82:83]
	v_lshl_add_u64 v[82:83], v[6:7], 0, v[82:83]
	global_load_dword v74, v[82:83], off
	v_add_u32_e32 v76, 60, v59
	v_mov_b32_e32 v84, v76
	v_mov_b32_e32 v85, 0
	v_lshlrev_b64 v[84:85], 12, v[84:85]
	v_lshl_add_u64 v[84:85], v[6:7], 0, v[84:85]
	global_load_dword v75, v[84:85], off
	s_waitcnt vmcnt(0)
	v_mul_lo_u32 v88, v58, s28
	v_add_u32_e32 v88, v88, v4
	ds_write_b32 v88, v60
	v_add_u32_e32 v86, 4, v58
	v_mul_lo_u32 v88, v86, s28
	v_add_u32_e32 v88, v88, v4
	ds_write_b32 v88, v61
	v_add_u32_e32 v86, 8, v58
	v_mul_lo_u32 v88, v86, s28
	v_add_u32_e32 v88, v88, v4
	ds_write_b32 v88, v62
	v_add_u32_e32 v86, 12, v58
	v_mul_lo_u32 v88, v86, s28
	v_add_u32_e32 v88, v88, v4
	ds_write_b32 v88, v63
	v_add_u32_e32 v86, 16, v58
	v_mul_lo_u32 v88, v86, s28
	v_add_u32_e32 v88, v88, v4
	ds_write_b32 v88, v64
	v_add_u32_e32 v86, 20, v58
	v_mul_lo_u32 v88, v86, s28
	v_add_u32_e32 v88, v88, v4
	ds_write_b32 v88, v65
	v_add_u32_e32 v86, 24, v58
	v_mul_lo_u32 v88, v86, s28
	v_add_u32_e32 v88, v88, v4
	ds_write_b32 v88, v66
	v_add_u32_e32 v86, 28, v58
	v_mul_lo_u32 v88, v86, s28
	v_add_u32_e32 v88, v88, v4
	ds_write_b32 v88, v67
	v_add_u32_e32 v86, 32, v58
	v_mul_lo_u32 v88, v86, s28
	v_add_u32_e32 v88, v88, v4
	ds_write_b32 v88, v68
	v_add_u32_e32 v86, 36, v58
	v_mul_lo_u32 v88, v86, s28
	v_add_u32_e32 v88, v88, v4
	ds_write_b32 v88, v69
	v_add_u32_e32 v86, 40, v58
	v_mul_lo_u32 v88, v86, s28
	v_add_u32_e32 v88, v88, v4
	ds_write_b32 v88, v70
	v_add_u32_e32 v86, 44, v58
	v_mul_lo_u32 v88, v86, s28
	v_add_u32_e32 v88, v88, v4
	ds_write_b32 v88, v71
	v_add_u32_e32 v86, 48, v58
	v_mul_lo_u32 v88, v86, s28
	v_add_u32_e32 v88, v88, v4
	ds_write_b32 v88, v72
	v_add_u32_e32 v86, 52, v58
	v_mul_lo_u32 v88, v86, s28
	v_add_u32_e32 v88, v88, v4
	ds_write_b32 v88, v73
	v_add_u32_e32 v86, 56, v58
	v_mul_lo_u32 v88, v86, s28
	v_add_u32_e32 v88, v88, v4
	ds_write_b32 v88, v74
	v_add_u32_e32 v86, 60, v58
	v_mul_lo_u32 v88, v86, s28
	v_add_u32_e32 v88, v88, v4
	ds_write_b32 v88, v75

.LBB0_44:
	s_and_b64 vcc, exec, s[4:5]
	s_cbranch_vccz .LBB0_63
	s_add_i32 s4, s37, 0xfffffc70
	v_mov_b32_e32 v2, v172
	s_lshr_b32 s38, s4, 4
	s_nop 0
	v_cmp_gt_i32_e32 vcc, s26, v2
	s_and_saveexec_b64 s[18:19], vcc
	s_cbranch_execz .LBB0_58
	s_lshl_b64 s[4:5], s[6:7], 2
	v_lshlrev_b32_e32 v0, 2, v2
	s_add_u32 s4, s54, s4
	v_and_b32_e32 v4, 0xfc, v0
	s_addc_u32 s5, s55, s5
	v_lshl_or_b32 v0, s11, 8, v4
	v_lshl_add_u64 v[6:7], s[4:5], 0, v[0:1]
	s_lshl_b32 s39, s38, 6
	v_ashrrev_i32_e32 v58, 6, v2
	v_add_u32_e32 v59, s39, v58
	v_mov_b32_e32 v78, v59
	v_mov_b32_e32 v79, 0
	v_lshlrev_b64 v[78:79], 12, v[78:79]
	v_lshl_add_u64 v[78:79], v[6:7], 0, v[78:79]
	global_load_dword v60, v[78:79], off
	v_add_u32_e32 v76, 4, v59
	v_mov_b32_e32 v80, v76
	v_mov_b32_e32 v81, 0
	v_lshlrev_b64 v[80:81], 12, v[80:81]
	v_lshl_add_u64 v[80:81], v[6:7], 0, v[80:81]
	global_load_dword v61, v[80:81], off
	v_add_u32_e32 v76, 8, v59
	v_mov_b32_e32 v82, v76
	v_mov_b32_e32 v83, 0
	v_lshlrev_b64 v[82:83], 12, v[82:83]
	v_lshl_add_u64 v[82:83], v[6:7], 0, v[82:83]
	global_load_dword v62, v[82:83], off
	v_add_u32_e32 v76, 12, v59
	v_mov_b32_e32 v84, v76
	v_mov_b32_e32 v85, 0
	v_lshlrev_b64 v[84:85], 12, v[84:85]
	v_lshl_add_u64 v[84:85], v[6:7], 0, v[84:85]
	global_load_dword v63, v[84:85], off
	v_add_u32_e32 v76, 16, v59
	v_mov_b32_e32 v78, v76
	v_mov_b32_e32 v79, 0
	v_lshlrev_b64 v[78:79], 12, v[78:79]
	v_lshl_add_u64 v[78:79], v[6:7], 0, v[78:79]
	global_load_dword v64, v[78:79], off
	v_add_u32_e32 v76, 20, v59
	v_mov_b32_e32 v80, v76
	v_mov_b32_e32 v81, 0
	v_lshlrev_b64 v[80:81], 12, v[80:81]
	v_lshl_add_u64 v[80:81], v[6:7], 0, v[80:81]
	global_load_dword v65, v[80:81], off
	v_add_u32_e32 v76, 24, v59
	v_mov_b32_e32 v82, v76
	v_mov_b32_e32 v83, 0
	v_lshlrev_b64 v[82:83], 12, v[82:83]
	v_lshl_add_u64 v[82:83], v[6:7], 0, v[82:83]
	global_load_dword v66, v[82:83], off
	v_add_u32_e32 v76, 28, v59
	v_mov_b32_e32 v84, v76
	v_mov_b32_e32 v85, 0
	v_lshlrev_b64 v[84:85], 12, v[84:85]
	v_lshl_add_u64 v[84:85], v[6:7], 0, v[84:85]
	global_load_dword v67, v[84:85], off
	v_add_u32_e32 v76, 32, v59
	v_mov_b32_e32 v78, v76
	v_mov_b32_e32 v79, 0
	v_lshlrev_b64 v[78:79], 12, v[78:79]
	v_lshl_add_u64 v[78:79], v[6:7], 0, v[78:79]
	global_load_dword v68, v[78:79], off
	v_add_u32_e32 v76, 36, v59
	v_mov_b32_e32 v80, v76
	v_mov_b32_e32 v81, 0
	v_lshlrev_b64 v[80:81], 12, v[80:81]
	v_lshl_add_u64 v[80:81], v[6:7], 0, v[80:81]
	global_load_dword v69, v[80:81], off
	v_add_u32_e32 v76, 40, v59
	v_mov_b32_e32 v82, v76
	v_mov_b32_e32 v83, 0
	v_lshlrev_b64 v[82:83], 12, v[82:83]
	v_lshl_add_u64 v[82:83], v[6:7], 0, v[82:83]
	global_load_dword v70, v[82:83], off
	v_add_u32_e32 v76, 44, v59
	v_mov_b32_e32 v84, v76
	v_mov_b32_e32 v85, 0
	v_lshlrev_b64 v[84:85], 12, v[84:85]
	v_lshl_add_u64 v[84:85], v[6:7], 0, v[84:85]
	global_load_dword v71, v[84:85], off
	v_add_u32_e32 v76, 48, v59
	v_mov_b32_e32 v78, v76
	v_mov_b32_e32 v79, 0
	v_lshlrev_b64 v[78:79], 12, v[78:79]
	v_lshl_add_u64 v[78:79], v[6:7], 0, v[78:79]
	global_load_dword v72, v[78:79], off
	v_add_u32_e32 v76, 52, v59
	v_mov_b32_e32 v80, v76
	v_mov_b32_e32 v81, 0
	v_lshlrev_b64 v[80:81], 12, v[80:81]
	v_lshl_add_u64 v[80:81], v[6:7], 0, v[80:81]
	global_load_dword v73, v[80:81], off
	v_add_u32_e32 v76, 56, v59
	v_mov_b32_e32 v82, v76
	v_mov_b32_e32 v83, 0
	v_lshlrev_b64 v[82:83], 12, v[82:83]
	v_lshl_add_u64 v[82:83], v[6:7], 0, v[82:83]
	global_load_dword v74, v[82:83], off
	v_add_u32_e32 v76, 60, v59
	v_mov_b32_e32 v84, v76
	v_mov_b32_e32 v85, 0
	v_lshlrev_b64 v[84:85], 12, v[84:85]
	v_lshl_add_u64 v[84:85], v[6:7], 0, v[84:85]
	global_load_dword v75, v[84:85], off
	s_waitcnt vmcnt(0)
	v_mul_lo_u32 v88, v58, s28
	v_add_u32_e32 v88, v88, v4
	ds_write_b32 v88, v60
	v_add_u32_e32 v86, 4, v58
	v_mul_lo_u32 v88, v86, s28
	v_add_u32_e32 v88, v88, v4
	ds_write_b32 v88, v61
	v_add_u32_e32 v86, 8, v58
	v_mul_lo_u32 v88, v86, s28
	v_add_u32_e32 v88, v88, v4
	ds_write_b32 v88, v62
	v_add_u32_e32 v86, 12, v58
	v_mul_lo_u32 v88, v86, s28
	v_add_u32_e32 v88, v88, v4
	ds_write_b32 v88, v63
	v_add_u32_e32 v86, 16, v58
	v_mul_lo_u32 v88, v86, s28
	v_add_u32_e32 v88, v88, v4
	ds_write_b32 v88, v64
	v_add_u32_e32 v86, 20, v58
	v_mul_lo_u32 v88, v86, s28
	v_add_u32_e32 v88, v88, v4
	ds_write_b32 v88, v65
	v_add_u32_e32 v86, 24, v58
	v_mul_lo_u32 v88, v86, s28
	v_add_u32_e32 v88, v88, v4
	ds_write_b32 v88, v66
	v_add_u32_e32 v86, 28, v58
	v_mul_lo_u32 v88, v86, s28
	v_add_u32_e32 v88, v88, v4
	ds_write_b32 v88, v67
	v_add_u32_e32 v86, 32, v58
	v_mul_lo_u32 v88, v86, s28
	v_add_u32_e32 v88, v88, v4
	ds_write_b32 v88, v68
	v_add_u32_e32 v86, 36, v58
	v_mul_lo_u32 v88, v86, s28
	v_add_u32_e32 v88, v88, v4
	ds_write_b32 v88, v69
	v_add_u32_e32 v86, 40, v58
	v_mul_lo_u32 v88, v86, s28
	v_add_u32_e32 v88, v88, v4
	ds_write_b32 v88, v70
	v_add_u32_e32 v86, 44, v58
	v_mul_lo_u32 v88, v86, s28
	v_add_u32_e32 v88, v88, v4
	ds_write_b32 v88, v71
	v_add_u32_e32 v86, 48, v58
	v_mul_lo_u32 v88, v86, s28
	v_add_u32_e32 v88, v88, v4
	ds_write_b32 v88, v72
	v_add_u32_e32 v86, 52, v58
	v_mul_lo_u32 v88, v86, s28
	v_add_u32_e32 v88, v88, v4
	ds_write_b32 v88, v73
	v_add_u32_e32 v86, 56, v58
	v_mul_lo_u32 v88, v86, s28
	v_add_u32_e32 v88, v88, v4
	ds_write_b32 v88, v74
	v_add_u32_e32 v86, 60, v58
	v_mul_lo_u32 v88, v86, s28
	v_add_u32_e32 v88, v88, v4
	ds_write_b32 v88, v75

.LBB0_93:
	s_mul_i32 s4, s37, 0x4d49
	s_lshr_b32 s5, s4, 31
	s_ashr_i32 s11, s4, 20
	s_add_i32 s11, s11, s5
	s_mul_i32 s4, s11, 53
	s_sub_i32 s4, s37, s4
	v_mov_b32_e32 v6, v172
	s_sext_i32_i16 s22, s4
	s_nop 0
	v_cmp_gt_i32_e32 vcc, s26, v6
	v_and_b32_e32 v4, 63, v6
	s_and_saveexec_b64 s[18:19], vcc
	s_cbranch_execz .LBB0_98
	s_mul_i32 s5, s10, 0xd18000
	s_mul_hi_i32 s4, s10, 0xd18000
	s_add_u32 s6, s52, s5
	v_lshl_or_b32 v2, s22, 6, v4
	s_addc_u32 s7, s53, s4
	v_ashrrev_i32_e32 v3, 31, v2
	s_lshl_b32 s23, s11, 6
	v_cmp_gt_i32_e64 s[4:5], s34, v2
	v_lshl_add_u64 v[2:3], v[2:3], 2, s[6:7]
	v_lshlrev_b32_e32 v0, 2, v4
	s_mov_b64 s[20:21], 0
	v_mov_b32_e32 v5, v6
	v_ashrrev_i32_e32 v58, 6, v6
	v_add_u32_e32 v59, s23, v58
	v_mov_b32_e32 v60, 0
	v_mov_b32_e32 v61, 0
	v_mov_b32_e32 v62, 0
	v_mov_b32_e32 v63, 0
	v_mov_b32_e32 v64, 0
	v_mov_b32_e32 v65, 0
	v_mov_b32_e32 v66, 0
	v_mov_b32_e32 v67, 0
	v_mov_b32_e32 v68, 0
	v_mov_b32_e32 v69, 0
	v_mov_b32_e32 v70, 0
	v_mov_b32_e32 v71, 0
	v_mov_b32_e32 v72, 0
	v_mov_b32_e32 v73, 0
	v_mov_b32_e32 v74, 0
	v_mov_b32_e32 v75, 0
	s_and_saveexec_b64 s[6:7], s[4:5]
	s_cbranch_execz .Lwin_skip
	v_mad_i64_i32 v[78:79], s[24:25], v59, s35, v[2:3]
	global_load_dword v60, v[78:79], off
	v_add_u32_e32 v76, 4, v59
	v_mad_i64_i32 v[80:81], s[24:25], v76, s35, v[2:3]
	global_load_dword v61, v[80:81], off
	v_add_u32_e32 v76, 8, v59
	v_mad_i64_i32 v[82:83], s[24:25], v76, s35, v[2:3]
	global_load_dword v62, v[82:83], off
	v_add_u32_e32 v76, 12, v59
	v_mad_i64_i32 v[84:85], s[24:25], v76, s35, v[2:3]
	global_load_dword v63, v[84:85], off
	v_add_u32_e32 v76, 16, v59
	v_mad_i64_i32 v[78:79], s[24:25], v76, s35, v[2:3]
	global_load_dword v64, v[78:79], off
	v_add_u32_e32 v76, 20, v59
	v_mad_i64_i32 v[80:81], s[24:25], v76, s35, v[2:3]
	global_load_dword v65, v[80:81], off
	v_add_u32_e32 v76, 24, v59
	v_mad_i64_i32 v[82:83], s[24:25], v76, s35, v[2:3]
	global_load_dword v66, v[82:83], off
	v_add_u32_e32 v76, 28, v59
	v_mad_i64_i32 v[84:85], s[24:25], v76, s35, v[2:3]
	global_load_dword v67, v[84:85], off
	v_add_u32_e32 v76, 32, v59
	v_mad_i64_i32 v[78:79], s[24:25], v76, s35, v[2:3]
	global_load_dword v68, v[78:79], off
	v_add_u32_e32 v76, 36, v59
	v_mad_i64_i32 v[80:81], s[24:25], v76, s35, v[2:3]
	global_load_dword v69, v[80:81], off
	v_add_u32_e32 v76, 40, v59
	v_mad_i64_i32 v[82:83], s[24:25], v76, s35, v[2:3]
	global_load_dword v70, v[82:83], off
	v_add_u32_e32 v76, 44, v59
	v_mad_i64_i32 v[84:85], s[24:25], v76, s35, v[2:3]
	global_load_dword v71, v[84:85], off
	v_add_u32_e32 v76, 48, v59
	v_mad_i64_i32 v[78:79], s[24:25], v76, s35, v[2:3]
	global_load_dword v72, v[78:79], off
	v_add_u32_e32 v76, 52, v59
	v_mad_i64_i32 v[80:81], s[24:25], v76, s35, v[2:3]
	global_load_dword v73, v[80:81], off
	v_add_u32_e32 v76, 56, v59
	v_mad_i64_i32 v[82:83], s[24:25], v76, s35, v[2:3]
	global_load_dword v74, v[82:83], off
	v_add_u32_e32 v76, 60, v59
	v_mad_i64_i32 v[84:85], s[24:25], v76, s35, v[2:3]
	global_load_dword v75, v[84:85], off
.Lwin_skip:
	s_or_b64 exec, exec, s[6:7]
	s_waitcnt vmcnt(0)
	v_mad_u64_u32 v[88:89], s[6:7], v58, s28, v[0:1]
	ds_write_b32 v88, v60
	v_add_u32_e32 v86, 4, v58
	v_mad_u64_u32 v[88:89], s[6:7], v86, s28, v[0:1]
	ds_write_b32 v88, v61
	v_add_u32_e32 v86, 8, v58
	v_mad_u64_u32 v[88:89], s[6:7], v86, s28, v[0:1]
	ds_write_b32 v88, v62
	v_add_u32_e32 v86, 12, v58
	v_mad_u64_u32 v[88:89], s[6:7], v86, s28, v[0:1]
	ds_write_b32 v88, v63
	v_add_u32_e32 v86, 16, v58
	v_mad_u64_u32 v[88:89], s[6:7], v86, s28, v[0:1]
	ds_write_b32 v88, v64
	v_add_u32_e32 v86, 20, v58
	v_mad_u64_u32 v[88:89], s[6:7], v86, s28, v[0:1]
	ds_write_b32 v88, v65
	v_add_u32_e32 v86, 24, v58
	v_mad_u64_u32 v[88:89], s[6:7], v86, s28, v[0:1]
	ds_write_b32 v88, v66
	v_add_u32_e32 v86, 28, v58
	v_mad_u64_u32 v[88:89], s[6:7], v86, s28, v[0:1]
	ds_write_b32 v88, v67
	v_add_u32_e32 v86, 32, v58
	v_mad_u64_u32 v[88:89], s[6:7], v86, s28, v[0:1]
	ds_write_b32 v88, v68
	v_add_u32_e32 v86, 36, v58
	v_mad_u64_u32 v[88:89], s[6:7], v86, s28, v[0:1]
	ds_write_b32 v88, v69
	v_add_u32_e32 v86, 40, v58
	v_mad_u64_u32 v[88:89], s[6:7], v86, s28, v[0:1]
	ds_write_b32 v88, v70
	v_add_u32_e32 v86, 44, v58
	v_mad_u64_u32 v[88:89], s[6:7], v86, s28, v[0:1]
	ds_write_b32 v88, v71
	v_add_u32_e32 v86, 48, v58
	v_mad_u64_u32 v[88:89], s[6:7], v86, s28, v[0:1]
	ds_write_b32 v88, v72
	v_add_u32_e32 v86, 52, v58
	v_mad_u64_u32 v[88:89], s[6:7], v86, s28, v[0:1]
	ds_write_b32 v88, v73
	v_add_u32_e32 v86, 56, v58
	v_mad_u64_u32 v[88:89], s[6:7], v86, s28, v[0:1]
	ds_write_b32 v88, v74
	v_add_u32_e32 v86, 60, v58
	v_mad_u64_u32 v[88:89], s[6:7], v86, s28, v[0:1]
	ds_write_b32 v88, v75
